# EpiRes GEMM epilogues (out, down): residual-base loads issued four at a time into dead fragment registers with counted vmcnt(3) instead of a load-wait-store ladder
# baseline (speedup 1.0000x reference)
;     __device__ __forceinline__ void operator()(const f32x4 (&acc)[2][2][4][2], const Unit& u, int wr, int wc, int fr, int fq) const {
;         const int row0 = u.pm * BM + wr * 64 + fr; const int b = batch_of_row(u.pm * BM); const int col0 = u.pn * BM + wc * 32 + 4 * fq;
;         f32x4 gv[2][2];
; #pragma unroll
;         for (int bj = 0; bj < 2; ++bj)
; #pragma unroll
;             for (int n = 0; n < 2; ++n) gv[bj][n] = *(const f32x4*)(gate + (size_t)b * 6144 + col0 + bj * HALF + n * 16);
; #pragma unroll
;         for (int ai = 0; ai < 2; ++ai)
; #pragma unroll
;             for (int m = 0; m < 4; ++m) { const int row = row0 + ai * HALF + m * 16;
;                 const float* bp = row < 32768 ? base_a + (size_t)row * 1024 : base_b + (size_t)(row - 32768) * 1024; float* op = out + (size_t)row * 1024;
; #pragma unroll
;                 for (int bj = 0; bj < 2; ++bj)
; #pragma unroll
;                     for (int n = 0; n < 2; ++n) { const int c = col0 + bj * HALF + n * 16; const f32x4 o = *(const f32x4*)(bp + c) + gv[bj][n] * acc[ai][bj][m][n]; *(f32x4*)(op + c) = o; }
;                 if (m & 1) asm volatile("" ::: "memory"); }
.LBB0_858:
	s_lshl_b32 s13, s75, 8
	s_min_i32 s0, s13, 0x8000
	s_ashr_i32 s0, s0, 11
	s_mul_hi_i32 s1, s0, 0x6000
	s_mulk_i32 s0, 0x6000
	v_lshl_or_b32 v170, s24, 8, v177
	s_add_u32 s0, s68, s0
	s_addc_u32 s1, s69, s1
	v_ashrrev_i32_e32 v171, 31, v170
	v_lshl_add_u64 v[114:115], v[170:171], 2, s[0:1]
	global_load_dwordx4 v[130:133], v[114:115], off
	global_load_dwordx4 v[126:129], v[114:115], off offset:64
	global_load_dwordx4 v[118:121], v[114:115], off offset:512
	s_nop 0
	global_load_dwordx4 v[114:117], v[114:115], off offset:576
	v_add_u32_e32 v168, s13, v1
	s_movk_i32 s13, 0x7fff
	v_cmp_lt_i32_e32 vcc, s13, v168
	s_and_saveexec_b64 s[0:1], vcc
	s_xor_b64 s[0:1], exec, s[0:1]
	v_readlane_b32 s85, v241, 5
	v_readlane_b32 s86, v241, 12
	v_readlane_b32 s89, v241, 13
	v_add_u32_e32 v172, 0xffff8000, v168
	v_mov_b32_e32 v173, v0
	v_lshlrev_b64 v[172:173], 12, v[172:173]
	v_mov_b32_e32 v169, v0
	v_lshl_add_u64 v[172:173], s[8:9], 0, v[172:173]
	v_lshlrev_b64 v[174:175], 12, v[168:169]
	s_andn2_saveexec_b64 s[0:1], s[0:1]
	v_ashrrev_i32_e32 v169, 31, v168
	v_lshlrev_b64 v[174:175], 12, v[168:169]
	v_lshl_add_u64 v[172:173], s[6:7], 0, v[174:175]
	s_or_b64 exec, exec, s[0:1]
	v_lshlrev_b64 v[170:171], 2, v[170:171]
	v_lshl_add_u64 v[172:173], v[172:173], 0, v[170:171]
	global_load_dwordx4 v[188:191], v[172:173], off
	global_load_dwordx4 v[192:195], v[172:173], off offset:64
	global_load_dwordx4 v[196:199], v[172:173], off offset:512
	global_load_dwordx4 v[200:203], v[172:173], off offset:576
	v_lshl_add_u64 v[174:175], s[48:49], 0, v[174:175]
	v_lshl_add_u64 v[174:175], v[174:175], 0, v[170:171]
	s_waitcnt vmcnt(3)
	v_pk_fma_f32 v[144:145], v[144:145], v[132:133], v[190:191]
	v_pk_fma_f32 v[142:143], v[142:143], v[130:131], v[188:189]
	global_store_dwordx4 v[174:175], v[142:145], off
	s_waitcnt vmcnt(3)
	v_pk_fma_f32 v[140:141], v[140:141], v[128:129], v[194:195]
	v_pk_fma_f32 v[138:139], v[138:139], v[126:127], v[192:193]
	global_store_dwordx4 v[174:175], v[138:141], off offset:64
	s_waitcnt vmcnt(3)
	v_pk_fma_f32 v[136:137], v[136:137], v[120:121], v[198:199]
	v_pk_fma_f32 v[134:135], v[134:135], v[118:119], v[196:197]
	global_store_dwordx4 v[174:175], v[134:137], off offset:512
	s_waitcnt vmcnt(3)
	v_pk_fma_f32 v[124:125], v[124:125], v[116:117], v[202:203]
	v_or_b32_e32 v134, 16, v168
	v_pk_fma_f32 v[122:123], v[122:123], v[114:115], v[200:201]
	v_cmp_lt_i32_e32 vcc, s13, v134
	global_store_dwordx4 v[174:175], v[122:125], off offset:576
	s_and_saveexec_b64 s[0:1], vcc
	s_xor_b64 s[0:1], exec, s[0:1]
	v_add_u32_e32 v122, 0xffff8010, v168
	v_mov_b32_e32 v123, v0
	v_lshlrev_b64 v[122:123], 12, v[122:123]
	v_mov_b32_e32 v135, v0
	v_lshl_add_u64 v[122:123], s[8:9], 0, v[122:123]
	v_lshlrev_b64 v[124:125], 12, v[134:135]
	s_andn2_saveexec_b64 s[0:1], s[0:1]
	v_ashrrev_i32_e32 v135, 31, v134
	v_lshlrev_b64 v[124:125], 12, v[134:135]
	v_lshl_add_u64 v[122:123], s[6:7], 0, v[124:125]
	s_or_b64 exec, exec, s[0:1]
	v_lshl_add_u64 v[122:123], v[122:123], 0, v[170:171]
	global_load_dwordx4 v[188:191], v[122:123], off
	global_load_dwordx4 v[192:195], v[122:123], off offset:64
	global_load_dwordx4 v[196:199], v[122:123], off offset:512
	global_load_dwordx4 v[200:203], v[122:123], off offset:576
	v_lshl_add_u64 v[124:125], s[48:49], 0, v[124:125]
	v_lshl_add_u64 v[124:125], v[124:125], 0, v[170:171]
	s_waitcnt vmcnt(3)
	v_pk_fma_f32 v[112:113], v[112:113], v[132:133], v[190:191]
	v_pk_fma_f32 v[110:111], v[110:111], v[130:131], v[188:189]
	global_store_dwordx4 v[124:125], v[110:113], off
	s_waitcnt vmcnt(3)
	v_pk_fma_f32 v[108:109], v[108:109], v[128:129], v[194:195]
	v_pk_fma_f32 v[106:107], v[106:107], v[126:127], v[192:193]
	global_store_dwordx4 v[124:125], v[106:109], off offset:64
	s_waitcnt vmcnt(3)
	v_pk_fma_f32 v[104:105], v[104:105], v[120:121], v[198:199]
	v_pk_fma_f32 v[102:103], v[102:103], v[118:119], v[196:197]
	global_store_dwordx4 v[124:125], v[102:105], off offset:512
	s_waitcnt vmcnt(3)
	v_pk_fma_f32 v[100:101], v[100:101], v[116:117], v[202:203]
	v_pk_fma_f32 v[98:99], v[98:99], v[114:115], v[200:201]
	global_store_dwordx4 v[124:125], v[98:101], off offset:576
	s_nop 1
	v_or_b32_e32 v98, 32, v168
	v_cmp_lt_i32_e32 vcc, s13, v98
	s_and_saveexec_b64 s[0:1], vcc
	s_xor_b64 s[0:1], exec, s[0:1]
	v_add_u32_e32 v100, 0xffff8020, v168
	v_mov_b32_e32 v101, v0
	v_lshlrev_b64 v[100:101], 12, v[100:101]
	v_mov_b32_e32 v99, v0
	v_lshl_add_u64 v[100:101], s[8:9], 0, v[100:101]
	v_lshlrev_b64 v[102:103], 12, v[98:99]
	s_andn2_saveexec_b64 s[0:1], s[0:1]
	v_ashrrev_i32_e32 v99, 31, v98
	v_lshlrev_b64 v[102:103], 12, v[98:99]
	v_lshl_add_u64 v[100:101], s[6:7], 0, v[102:103]
	s_or_b64 exec, exec, s[0:1]
	v_lshl_add_u64 v[104:105], v[100:101], 0, v[170:171]
	global_load_dwordx4 v[188:191], v[104:105], off
	global_load_dwordx4 v[192:195], v[104:105], off offset:64
	global_load_dwordx4 v[196:199], v[104:105], off offset:512
	global_load_dwordx4 v[200:203], v[104:105], off offset:576
	v_lshl_add_u64 v[102:103], s[48:49], 0, v[102:103]
	v_lshl_add_u64 v[102:103], v[102:103], 0, v[170:171]
	s_waitcnt vmcnt(3)
	v_pk_fma_f32 v[96:97], v[96:97], v[132:133], v[190:191]
	v_pk_fma_f32 v[94:95], v[94:95], v[130:131], v[188:189]
	global_store_dwordx4 v[102:103], v[94:97], off
	s_waitcnt vmcnt(3)
	v_pk_fma_f32 v[92:93], v[92:93], v[128:129], v[194:195]
	v_pk_fma_f32 v[90:91], v[90:91], v[126:127], v[192:193]
	global_store_dwordx4 v[102:103], v[90:93], off offset:64
	s_waitcnt vmcnt(3)
	v_pk_fma_f32 v[88:89], v[88:89], v[120:121], v[198:199]
	v_pk_fma_f32 v[86:87], v[86:87], v[118:119], v[196:197]
	global_store_dwordx4 v[102:103], v[86:89], off offset:512
	s_waitcnt vmcnt(3)
;     __device__ __forceinline__ void operator()(const f32x4 (&acc)[2][2][4][2], const Unit& u, int wr, int wc, int fr, int fq) const {
;     ...
;             for (int m = 0; m < 4; ++m) { const int row = row0 + ai * HALF + m * 16;
;                 const float* bp = row < 32768 ? base_a + (size_t)row * 1024 : base_b + (size_t)(row - 32768) * 1024; float* op = out + (size_t)row * 1024;
; #pragma unroll
;                 for (int bj = 0; bj < 2; ++bj)
; #pragma unroll
;                     for (int n = 0; n < 2; ++n) { const int c = col0 + bj * HALF + n * 16; const f32x4 o = *(const f32x4*)(bp + c) + gv[bj][n] * acc[ai][bj][m][n]; *(f32x4*)(op + c) = o; }
;                 if (m & 1) asm volatile("" ::: "memory"); }
	v_pk_fma_f32 v[84:85], v[84:85], v[116:117], v[202:203]
	v_or_b32_e32 v86, 48, v168
	v_pk_fma_f32 v[82:83], v[82:83], v[114:115], v[200:201]
	v_cmp_lt_i32_e32 vcc, s13, v86
	global_store_dwordx4 v[102:103], v[82:85], off offset:576
	s_and_saveexec_b64 s[0:1], vcc
	s_xor_b64 s[0:1], exec, s[0:1]
	v_add_u32_e32 v82, 0xffff8030, v168
	v_mov_b32_e32 v83, v0
	v_lshlrev_b64 v[82:83], 12, v[82:83]
	v_mov_b32_e32 v87, v0
	v_lshl_add_u64 v[82:83], s[8:9], 0, v[82:83]
	v_lshlrev_b64 v[84:85], 12, v[86:87]
	s_andn2_saveexec_b64 s[0:1], s[0:1]
	v_ashrrev_i32_e32 v87, 31, v86
	v_lshlrev_b64 v[84:85], 12, v[86:87]
	v_lshl_add_u64 v[82:83], s[6:7], 0, v[84:85]
	s_or_b64 exec, exec, s[0:1]
	v_lshl_add_u64 v[82:83], v[82:83], 0, v[170:171]
	global_load_dwordx4 v[188:191], v[82:83], off
	global_load_dwordx4 v[192:195], v[82:83], off offset:64
	global_load_dwordx4 v[196:199], v[82:83], off offset:512
	global_load_dwordx4 v[200:203], v[82:83], off offset:576
	v_lshl_add_u64 v[84:85], s[48:49], 0, v[84:85]
	v_lshl_add_u64 v[84:85], v[84:85], 0, v[170:171]
	s_movk_i32 s0, 0x7f7f
	v_cmp_lt_i32_e32 vcc, s0, v168
	s_waitcnt vmcnt(3)
	v_pk_fma_f32 v[80:81], v[80:81], v[132:133], v[190:191]
	v_pk_fma_f32 v[78:79], v[78:79], v[130:131], v[188:189]
	global_store_dwordx4 v[84:85], v[78:81], off
	s_waitcnt vmcnt(3)
	v_pk_fma_f32 v[76:77], v[76:77], v[128:129], v[194:195]
	v_pk_fma_f32 v[74:75], v[74:75], v[126:127], v[192:193]
	global_store_dwordx4 v[84:85], v[74:77], off offset:64
	s_waitcnt vmcnt(3)
	v_pk_fma_f32 v[72:73], v[72:73], v[120:121], v[198:199]
	v_pk_fma_f32 v[70:71], v[70:71], v[118:119], v[196:197]
	global_store_dwordx4 v[84:85], v[70:73], off offset:512
	s_waitcnt vmcnt(3)
	v_pk_fma_f32 v[68:69], v[68:69], v[116:117], v[202:203]
	v_pk_fma_f32 v[66:67], v[66:67], v[114:115], v[200:201]
	global_store_dwordx4 v[84:85], v[66:69], off offset:576
	s_nop 1
	v_add_u32_e32 v66, 0x80, v168
	s_and_saveexec_b64 s[0:1], vcc
	s_xor_b64 s[0:1], exec, s[0:1]
	v_add_u32_e32 v68, 0xffff8080, v168
	v_mov_b32_e32 v69, v0
	v_lshlrev_b64 v[68:69], 12, v[68:69]
	v_mov_b32_e32 v67, v0
	v_lshl_add_u64 v[68:69], s[8:9], 0, v[68:69]
	v_lshlrev_b64 v[70:71], 12, v[66:67]
	s_andn2_saveexec_b64 s[0:1], s[0:1]
	v_ashrrev_i32_e32 v67, 31, v66
	v_lshlrev_b64 v[70:71], 12, v[66:67]
	v_lshl_add_u64 v[68:69], s[6:7], 0, v[70:71]
	s_or_b64 exec, exec, s[0:1]
	v_lshl_add_u64 v[72:73], v[68:69], 0, v[170:171]
	global_load_dwordx4 v[188:191], v[72:73], off
	global_load_dwordx4 v[192:195], v[72:73], off offset:64
	global_load_dwordx4 v[196:199], v[72:73], off offset:512
	global_load_dwordx4 v[200:203], v[72:73], off offset:576
	v_lshl_add_u64 v[70:71], s[48:49], 0, v[70:71]
	v_lshl_add_u64 v[70:71], v[70:71], 0, v[170:171]
	s_movk_i32 s0, 0x7f6f
	v_cmp_lt_i32_e32 vcc, s0, v168
	s_waitcnt vmcnt(3)
	v_pk_fma_f32 v[64:65], v[64:65], v[132:133], v[190:191]
	v_pk_fma_f32 v[62:63], v[62:63], v[130:131], v[188:189]
	global_store_dwordx4 v[70:71], v[62:65], off
	s_waitcnt vmcnt(3)
	v_pk_fma_f32 v[60:61], v[60:61], v[128:129], v[194:195]
	v_pk_fma_f32 v[58:59], v[58:59], v[126:127], v[192:193]
	global_store_dwordx4 v[70:71], v[58:61], off offset:64
	s_waitcnt vmcnt(3)
	v_pk_fma_f32 v[56:57], v[56:57], v[120:121], v[198:199]
	v_pk_fma_f32 v[54:55], v[54:55], v[118:119], v[196:197]
	global_store_dwordx4 v[70:71], v[54:57], off offset:512
	s_waitcnt vmcnt(3)
	v_pk_fma_f32 v[52:53], v[52:53], v[116:117], v[202:203]
	v_add_u32_e32 v54, 0x90, v168
	v_pk_fma_f32 v[50:51], v[50:51], v[114:115], v[200:201]
	global_store_dwordx4 v[70:71], v[50:53], off offset:576
	s_and_saveexec_b64 s[0:1], vcc
	s_xor_b64 s[0:1], exec, s[0:1]
	v_add_u32_e32 v50, 0xffff8090, v168
	v_mov_b32_e32 v51, v0
	v_lshlrev_b64 v[50:51], 12, v[50:51]
	v_mov_b32_e32 v55, v0
	v_lshl_add_u64 v[50:51], s[8:9], 0, v[50:51]
	v_lshlrev_b64 v[52:53], 12, v[54:55]
	s_andn2_saveexec_b64 s[0:1], s[0:1]
	v_ashrrev_i32_e32 v55, 31, v54
	v_lshlrev_b64 v[52:53], 12, v[54:55]
	v_lshl_add_u64 v[50:51], s[6:7], 0, v[52:53]
	s_or_b64 exec, exec, s[0:1]
	v_lshl_add_u64 v[50:51], v[50:51], 0, v[170:171]
	global_load_dwordx4 v[188:191], v[50:51], off
	global_load_dwordx4 v[192:195], v[50:51], off offset:64
	global_load_dwordx4 v[196:199], v[50:51], off offset:512
	global_load_dwordx4 v[200:203], v[50:51], off offset:576
	v_lshl_add_u64 v[52:53], s[48:49], 0, v[52:53]
	v_lshl_add_u64 v[52:53], v[52:53], 0, v[170:171]
	s_movk_i32 s0, 0x7f5f
	v_cmp_lt_i32_e32 vcc, s0, v168
	s_waitcnt vmcnt(3)
;     __device__ __forceinline__ void operator()(const f32x4 (&acc)[2][2][4][2], const Unit& u, int wr, int wc, int fr, int fq) const {
;     ...
;             for (int m = 0; m < 4; ++m) { const int row = row0 + ai * HALF + m * 16;
;                 const float* bp = row < 32768 ? base_a + (size_t)row * 1024 : base_b + (size_t)(row - 32768) * 1024; float* op = out + (size_t)row * 1024;
; #pragma unroll
;                 for (int bj = 0; bj < 2; ++bj)
; #pragma unroll
;                     for (int n = 0; n < 2; ++n) { const int c = col0 + bj * HALF + n * 16; const f32x4 o = *(const f32x4*)(bp + c) + gv[bj][n] * acc[ai][bj][m][n]; *(f32x4*)(op + c) = o; }
;                 if (m & 1) asm volatile("" ::: "memory"); }
; template <class Epi, class Sched, bool ALIGN_EPI = false, bool SP2 = false>
; __device__ __forceinline__ void gemm_phase(PG8_LAS unsigned char* lds, const Gemm g, const Sched& S, const Epi& E, int tid_in) {
;     ...
;         if constexpr (!Epi::AFTER_DRAIN) { E(acc, cur, wr, wc, fr, fq); S.done(cur); }
;         if (!has_next) break;
	v_pk_fma_f32 v[48:49], v[48:49], v[132:133], v[190:191]
	v_pk_fma_f32 v[46:47], v[46:47], v[130:131], v[188:189]
	global_store_dwordx4 v[52:53], v[46:49], off
	s_waitcnt vmcnt(3)
	v_pk_fma_f32 v[44:45], v[44:45], v[128:129], v[194:195]
	v_pk_fma_f32 v[42:43], v[42:43], v[126:127], v[192:193]
	global_store_dwordx4 v[52:53], v[42:45], off offset:64
	s_waitcnt vmcnt(3)
	v_pk_fma_f32 v[40:41], v[40:41], v[120:121], v[198:199]
	v_pk_fma_f32 v[38:39], v[38:39], v[118:119], v[196:197]
	global_store_dwordx4 v[52:53], v[38:41], off offset:512
	s_waitcnt vmcnt(3)
	v_pk_fma_f32 v[36:37], v[36:37], v[116:117], v[202:203]
	v_pk_fma_f32 v[34:35], v[34:35], v[114:115], v[200:201]
	global_store_dwordx4 v[52:53], v[34:37], off offset:576
	s_nop 1
	v_add_u32_e32 v34, 0xa0, v168
	s_and_saveexec_b64 s[0:1], vcc
	s_xor_b64 s[0:1], exec, s[0:1]
	v_add_u32_e32 v36, 0xffff80a0, v168
	v_mov_b32_e32 v37, v0
	v_lshlrev_b64 v[36:37], 12, v[36:37]
	v_mov_b32_e32 v35, v0
	v_lshl_add_u64 v[36:37], s[8:9], 0, v[36:37]
	v_lshlrev_b64 v[38:39], 12, v[34:35]
	s_andn2_saveexec_b64 s[0:1], s[0:1]
	v_ashrrev_i32_e32 v35, 31, v34
	v_lshlrev_b64 v[38:39], 12, v[34:35]
	v_lshl_add_u64 v[36:37], s[6:7], 0, v[38:39]
	s_or_b64 exec, exec, s[0:1]
	v_lshl_add_u64 v[40:41], v[36:37], 0, v[170:171]
	global_load_dwordx4 v[188:191], v[40:41], off
	global_load_dwordx4 v[192:195], v[40:41], off offset:64
	global_load_dwordx4 v[196:199], v[40:41], off offset:512
	global_load_dwordx4 v[200:203], v[40:41], off offset:576
	v_lshl_add_u64 v[38:39], s[48:49], 0, v[38:39]
	v_lshl_add_u64 v[38:39], v[38:39], 0, v[170:171]
	s_movk_i32 s0, 0x7f4f
	v_cmp_lt_i32_e32 vcc, s0, v168
	s_waitcnt vmcnt(3)
	v_pk_fma_f32 v[32:33], v[32:33], v[132:133], v[190:191]
	v_pk_fma_f32 v[30:31], v[30:31], v[130:131], v[188:189]
	global_store_dwordx4 v[38:39], v[30:33], off
	s_waitcnt vmcnt(3)
	v_pk_fma_f32 v[28:29], v[28:29], v[128:129], v[194:195]
	v_pk_fma_f32 v[26:27], v[26:27], v[126:127], v[192:193]
	global_store_dwordx4 v[38:39], v[26:29], off offset:64
	s_waitcnt vmcnt(3)
	v_pk_fma_f32 v[24:25], v[24:25], v[120:121], v[198:199]
	v_pk_fma_f32 v[22:23], v[22:23], v[118:119], v[196:197]
	global_store_dwordx4 v[38:39], v[22:25], off offset:512
	s_waitcnt vmcnt(3)
	v_pk_fma_f32 v[20:21], v[20:21], v[116:117], v[202:203]
	v_add_u32_e32 v22, 0xb0, v168
	v_pk_fma_f32 v[18:19], v[18:19], v[114:115], v[200:201]
	global_store_dwordx4 v[38:39], v[18:21], off offset:576
	s_and_saveexec_b64 s[0:1], vcc
	s_xor_b64 s[0:1], exec, s[0:1]
	v_add_u32_e32 v18, 0xffff80b0, v168
	v_mov_b32_e32 v19, v0
	v_lshlrev_b64 v[18:19], 12, v[18:19]
	v_mov_b32_e32 v23, v0
	v_lshl_add_u64 v[18:19], s[8:9], 0, v[18:19]
	v_lshlrev_b64 v[20:21], 12, v[22:23]
	s_andn2_saveexec_b64 s[0:1], s[0:1]
	v_ashrrev_i32_e32 v23, 31, v22
	v_lshlrev_b64 v[20:21], 12, v[22:23]
	v_lshl_add_u64 v[18:19], s[6:7], 0, v[20:21]
	s_or_b64 exec, exec, s[0:1]
	v_lshl_add_u64 v[18:19], v[18:19], 0, v[170:171]
	global_load_dwordx4 v[188:191], v[18:19], off
	global_load_dwordx4 v[192:195], v[18:19], off offset:64
	global_load_dwordx4 v[196:199], v[18:19], off offset:512
	global_load_dwordx4 v[200:203], v[18:19], off offset:576
	v_lshl_add_u64 v[20:21], s[48:49], 0, v[20:21]
	v_lshl_add_u64 v[20:21], v[20:21], 0, v[170:171]
	s_andn2_b64 vcc, exec, s[44:45]
	s_mov_b64 s[0:1], -1
	s_waitcnt vmcnt(3)
	v_pk_fma_f32 v[16:17], v[16:17], v[132:133], v[190:191]
	v_pk_fma_f32 v[14:15], v[14:15], v[130:131], v[188:189]
	global_store_dwordx4 v[20:21], v[14:17], off
	s_waitcnt vmcnt(3)
	v_pk_fma_f32 v[12:13], v[12:13], v[128:129], v[194:195]
	v_pk_fma_f32 v[10:11], v[10:11], v[126:127], v[192:193]
	global_store_dwordx4 v[20:21], v[10:13], off offset:64
	s_waitcnt vmcnt(3)
	v_pk_fma_f32 v[8:9], v[8:9], v[120:121], v[198:199]
	v_pk_fma_f32 v[6:7], v[6:7], v[118:119], v[196:197]
	global_store_dwordx4 v[20:21], v[6:9], off offset:512
	s_waitcnt vmcnt(3)
	v_pk_fma_f32 v[4:5], v[4:5], v[116:117], v[202:203]
	v_pk_fma_f32 v[2:3], v[2:3], v[114:115], v[200:201]
	global_store_dwordx4 v[20:21], v[2:5], off offset:576
	s_cbranch_vccnz .LBB0_851
	s_andn2_b64 vcc, exec, s[2:3]
	s_cbranch_vccnz .LBB0_850
	s_barrier
	s_branch .LBB0_850

;     __device__ __forceinline__ void operator()(const f32x4 (&acc)[2][2][4][2], const Unit& u, int wr, int wc, int fr, int fq) const {
;         const int row0 = u.pm * BM + wr * 64 + fr; const int b = batch_of_row(u.pm * BM); const int col0 = u.pn * BM + wc * 32 + 4 * fq;
;         f32x4 gv[2][2];
; #pragma unroll
;         for (int bj = 0; bj < 2; ++bj)
; #pragma unroll
;             for (int n = 0; n < 2; ++n) gv[bj][n] = *(const f32x4*)(gate + (size_t)b * 6144 + col0 + bj * HALF + n * 16);
; #pragma unroll
;         for (int ai = 0; ai < 2; ++ai)
; #pragma unroll
;             for (int m = 0; m < 4; ++m) { const int row = row0 + ai * HALF + m * 16;
;                 const float* bp = row < 32768 ? base_a + (size_t)row * 1024 : base_b + (size_t)(row - 32768) * 1024; float* op = out + (size_t)row * 1024;
; #pragma unroll
;                 for (int bj = 0; bj < 2; ++bj)
; #pragma unroll
;                     for (int n = 0; n < 2; ++n) { const int c = col0 + bj * HALF + n * 16; const f32x4 o = *(const f32x4*)(bp + c) + gv[bj][n] * acc[ai][bj][m][n]; *(f32x4*)(op + c) = o; }
;                 if (m & 1) asm volatile("" ::: "memory"); }
.LBB0_1118:
	s_lshl_b32 s17, s66, 8
	s_min_i32 s0, s17, 0x8000
	s_ashr_i32 s0, s0, 11
	s_mul_hi_i32 s1, s0, 0x6000
	s_mulk_i32 s0, 0x6000
	v_lshl_or_b32 v170, s24, 8, v177
	s_add_u32 s0, s50, s0
	s_addc_u32 s1, s51, s1
	v_ashrrev_i32_e32 v171, 31, v170
	v_lshl_add_u64 v[114:115], v[170:171], 2, s[0:1]
	global_load_dwordx4 v[130:133], v[114:115], off
	global_load_dwordx4 v[126:129], v[114:115], off offset:64
	global_load_dwordx4 v[118:121], v[114:115], off offset:512
	s_nop 0
	global_load_dwordx4 v[114:117], v[114:115], off offset:576
	v_add_u32_e32 v168, s17, v1
	s_movk_i32 s17, 0x7fff
	v_cmp_lt_i32_e32 vcc, s17, v168
	s_and_saveexec_b64 s[0:1], vcc
	s_xor_b64 s[0:1], exec, s[0:1]
	v_readlane_b32 s69, v241, 11
	v_add_u32_e32 v172, 0xffff8000, v168
	v_mov_b32_e32 v173, v0
	v_lshlrev_b64 v[172:173], 12, v[172:173]
	v_mov_b32_e32 v169, v0
	v_lshl_add_u64 v[172:173], s[6:7], 0, v[172:173]
	v_lshlrev_b64 v[174:175], 12, v[168:169]
	s_andn2_saveexec_b64 s[0:1], s[0:1]
	v_ashrrev_i32_e32 v169, 31, v168
	v_lshlrev_b64 v[174:175], 12, v[168:169]
	v_lshl_add_u64 v[172:173], s[48:49], 0, v[174:175]
	s_or_b64 exec, exec, s[0:1]
	v_lshlrev_b64 v[170:171], 2, v[170:171]
	v_lshl_add_u64 v[172:173], v[172:173], 0, v[170:171]
	global_load_dwordx4 v[188:191], v[172:173], off
	global_load_dwordx4 v[192:195], v[172:173], off offset:64
	global_load_dwordx4 v[196:199], v[172:173], off offset:512
	global_load_dwordx4 v[200:203], v[172:173], off offset:576
	v_lshl_add_u64 v[174:175], s[48:49], 0, v[174:175]
	v_lshl_add_u64 v[174:175], v[174:175], 0, v[170:171]
	s_waitcnt vmcnt(3)
	v_pk_fma_f32 v[144:145], v[144:145], v[132:133], v[190:191]
	v_pk_fma_f32 v[142:143], v[142:143], v[130:131], v[188:189]
	global_store_dwordx4 v[174:175], v[142:145], off
	s_waitcnt vmcnt(3)
	v_pk_fma_f32 v[140:141], v[140:141], v[128:129], v[194:195]
	v_pk_fma_f32 v[138:139], v[138:139], v[126:127], v[192:193]
	global_store_dwordx4 v[174:175], v[138:141], off offset:64
	s_waitcnt vmcnt(3)
	v_pk_fma_f32 v[136:137], v[136:137], v[120:121], v[198:199]
	v_pk_fma_f32 v[134:135], v[134:135], v[118:119], v[196:197]
	global_store_dwordx4 v[174:175], v[134:137], off offset:512
	s_waitcnt vmcnt(3)
	v_pk_fma_f32 v[124:125], v[124:125], v[116:117], v[202:203]
	v_or_b32_e32 v134, 16, v168
	v_pk_fma_f32 v[122:123], v[122:123], v[114:115], v[200:201]
	v_cmp_lt_i32_e32 vcc, s17, v134
	global_store_dwordx4 v[174:175], v[122:125], off offset:576
	s_and_saveexec_b64 s[0:1], vcc
	s_xor_b64 s[0:1], exec, s[0:1]
	v_add_u32_e32 v122, 0xffff8010, v168
	v_mov_b32_e32 v123, v0
	v_lshlrev_b64 v[122:123], 12, v[122:123]
	v_mov_b32_e32 v135, v0
	v_lshl_add_u64 v[122:123], s[6:7], 0, v[122:123]
	v_lshlrev_b64 v[124:125], 12, v[134:135]
	s_andn2_saveexec_b64 s[0:1], s[0:1]
	v_ashrrev_i32_e32 v135, 31, v134
	v_lshlrev_b64 v[124:125], 12, v[134:135]
	v_lshl_add_u64 v[122:123], s[48:49], 0, v[124:125]
	s_or_b64 exec, exec, s[0:1]
	v_lshl_add_u64 v[122:123], v[122:123], 0, v[170:171]
	global_load_dwordx4 v[188:191], v[122:123], off
	global_load_dwordx4 v[192:195], v[122:123], off offset:64
	global_load_dwordx4 v[196:199], v[122:123], off offset:512
	global_load_dwordx4 v[200:203], v[122:123], off offset:576
	v_lshl_add_u64 v[124:125], s[48:49], 0, v[124:125]
	v_lshl_add_u64 v[124:125], v[124:125], 0, v[170:171]
	s_waitcnt vmcnt(3)
	v_pk_fma_f32 v[112:113], v[112:113], v[132:133], v[190:191]
	v_pk_fma_f32 v[110:111], v[110:111], v[130:131], v[188:189]
	global_store_dwordx4 v[124:125], v[110:113], off
	s_waitcnt vmcnt(3)
	v_pk_fma_f32 v[108:109], v[108:109], v[128:129], v[194:195]
	v_pk_fma_f32 v[106:107], v[106:107], v[126:127], v[192:193]
	global_store_dwordx4 v[124:125], v[106:109], off offset:64
	s_waitcnt vmcnt(3)
	v_pk_fma_f32 v[104:105], v[104:105], v[120:121], v[198:199]
	v_pk_fma_f32 v[102:103], v[102:103], v[118:119], v[196:197]
	global_store_dwordx4 v[124:125], v[102:105], off offset:512
	s_waitcnt vmcnt(3)
	v_pk_fma_f32 v[100:101], v[100:101], v[116:117], v[202:203]
	v_pk_fma_f32 v[98:99], v[98:99], v[114:115], v[200:201]
	global_store_dwordx4 v[124:125], v[98:101], off offset:576
	s_nop 1
	v_or_b32_e32 v98, 32, v168
	v_cmp_lt_i32_e32 vcc, s17, v98
	s_and_saveexec_b64 s[0:1], vcc
	s_xor_b64 s[0:1], exec, s[0:1]
	v_add_u32_e32 v100, 0xffff8020, v168
	v_mov_b32_e32 v101, v0
	v_lshlrev_b64 v[100:101], 12, v[100:101]
	v_mov_b32_e32 v99, v0
	v_lshl_add_u64 v[100:101], s[6:7], 0, v[100:101]
	v_lshlrev_b64 v[102:103], 12, v[98:99]
	s_andn2_saveexec_b64 s[0:1], s[0:1]
	v_ashrrev_i32_e32 v99, 31, v98
	v_lshlrev_b64 v[102:103], 12, v[98:99]
	v_lshl_add_u64 v[100:101], s[48:49], 0, v[102:103]
	s_or_b64 exec, exec, s[0:1]
	v_lshl_add_u64 v[104:105], v[100:101], 0, v[170:171]
	global_load_dwordx4 v[188:191], v[104:105], off
	global_load_dwordx4 v[192:195], v[104:105], off offset:64
	global_load_dwordx4 v[196:199], v[104:105], off offset:512
	global_load_dwordx4 v[200:203], v[104:105], off offset:576
	v_lshl_add_u64 v[102:103], s[48:49], 0, v[102:103]
	v_lshl_add_u64 v[102:103], v[102:103], 0, v[170:171]
	s_waitcnt vmcnt(3)
	v_pk_fma_f32 v[96:97], v[96:97], v[132:133], v[190:191]
	v_pk_fma_f32 v[94:95], v[94:95], v[130:131], v[188:189]
	global_store_dwordx4 v[102:103], v[94:97], off
	s_waitcnt vmcnt(3)
	v_pk_fma_f32 v[92:93], v[92:93], v[128:129], v[194:195]
	v_pk_fma_f32 v[90:91], v[90:91], v[126:127], v[192:193]
	global_store_dwordx4 v[102:103], v[90:93], off offset:64
	s_waitcnt vmcnt(3)
	v_pk_fma_f32 v[88:89], v[88:89], v[120:121], v[198:199]
	v_pk_fma_f32 v[86:87], v[86:87], v[118:119], v[196:197]
	global_store_dwordx4 v[102:103], v[86:89], off offset:512
	s_waitcnt vmcnt(3)
;     __device__ __forceinline__ void operator()(const f32x4 (&acc)[2][2][4][2], const Unit& u, int wr, int wc, int fr, int fq) const {
;     ...
;             for (int m = 0; m < 4; ++m) { const int row = row0 + ai * HALF + m * 16;
;                 const float* bp = row < 32768 ? base_a + (size_t)row * 1024 : base_b + (size_t)(row - 32768) * 1024; float* op = out + (size_t)row * 1024;
; #pragma unroll
;                 for (int bj = 0; bj < 2; ++bj)
; #pragma unroll
;                     for (int n = 0; n < 2; ++n) { const int c = col0 + bj * HALF + n * 16; const f32x4 o = *(const f32x4*)(bp + c) + gv[bj][n] * acc[ai][bj][m][n]; *(f32x4*)(op + c) = o; }
;                 if (m & 1) asm volatile("" ::: "memory"); }
	v_pk_fma_f32 v[84:85], v[84:85], v[116:117], v[202:203]
	v_or_b32_e32 v86, 48, v168
	v_pk_fma_f32 v[82:83], v[82:83], v[114:115], v[200:201]
	v_cmp_lt_i32_e32 vcc, s17, v86
	global_store_dwordx4 v[102:103], v[82:85], off offset:576
	s_and_saveexec_b64 s[0:1], vcc
	s_xor_b64 s[0:1], exec, s[0:1]
	v_add_u32_e32 v82, 0xffff8030, v168
	v_mov_b32_e32 v83, v0
	v_lshlrev_b64 v[82:83], 12, v[82:83]
	v_mov_b32_e32 v87, v0
	v_lshl_add_u64 v[82:83], s[6:7], 0, v[82:83]
	v_lshlrev_b64 v[84:85], 12, v[86:87]
	s_andn2_saveexec_b64 s[0:1], s[0:1]
	v_ashrrev_i32_e32 v87, 31, v86
	v_lshlrev_b64 v[84:85], 12, v[86:87]
	v_lshl_add_u64 v[82:83], s[48:49], 0, v[84:85]
	s_or_b64 exec, exec, s[0:1]
	v_lshl_add_u64 v[82:83], v[82:83], 0, v[170:171]
	global_load_dwordx4 v[188:191], v[82:83], off
	global_load_dwordx4 v[192:195], v[82:83], off offset:64
	global_load_dwordx4 v[196:199], v[82:83], off offset:512
	global_load_dwordx4 v[200:203], v[82:83], off offset:576
	v_lshl_add_u64 v[84:85], s[48:49], 0, v[84:85]
	v_lshl_add_u64 v[84:85], v[84:85], 0, v[170:171]
	s_movk_i32 s0, 0x7f7f
	v_cmp_lt_i32_e32 vcc, s0, v168
	s_waitcnt vmcnt(3)
	v_pk_fma_f32 v[80:81], v[80:81], v[132:133], v[190:191]
	v_pk_fma_f32 v[78:79], v[78:79], v[130:131], v[188:189]
	global_store_dwordx4 v[84:85], v[78:81], off
	s_waitcnt vmcnt(3)
	v_pk_fma_f32 v[76:77], v[76:77], v[128:129], v[194:195]
	v_pk_fma_f32 v[74:75], v[74:75], v[126:127], v[192:193]
	global_store_dwordx4 v[84:85], v[74:77], off offset:64
	s_waitcnt vmcnt(3)
	v_pk_fma_f32 v[72:73], v[72:73], v[120:121], v[198:199]
	v_pk_fma_f32 v[70:71], v[70:71], v[118:119], v[196:197]
	global_store_dwordx4 v[84:85], v[70:73], off offset:512
	s_waitcnt vmcnt(3)
	v_pk_fma_f32 v[68:69], v[68:69], v[116:117], v[202:203]
	v_pk_fma_f32 v[66:67], v[66:67], v[114:115], v[200:201]
	global_store_dwordx4 v[84:85], v[66:69], off offset:576
	s_nop 1
	v_add_u32_e32 v66, 0x80, v168
	s_and_saveexec_b64 s[0:1], vcc
	s_xor_b64 s[0:1], exec, s[0:1]
	v_add_u32_e32 v68, 0xffff8080, v168
	v_mov_b32_e32 v69, v0
	v_lshlrev_b64 v[68:69], 12, v[68:69]
	v_mov_b32_e32 v67, v0
	v_lshl_add_u64 v[68:69], s[6:7], 0, v[68:69]
	v_lshlrev_b64 v[70:71], 12, v[66:67]
	s_andn2_saveexec_b64 s[0:1], s[0:1]
	v_ashrrev_i32_e32 v67, 31, v66
	v_lshlrev_b64 v[70:71], 12, v[66:67]
	v_lshl_add_u64 v[68:69], s[48:49], 0, v[70:71]
	s_or_b64 exec, exec, s[0:1]
	v_lshl_add_u64 v[72:73], v[68:69], 0, v[170:171]
	global_load_dwordx4 v[188:191], v[72:73], off
	global_load_dwordx4 v[192:195], v[72:73], off offset:64
	global_load_dwordx4 v[196:199], v[72:73], off offset:512
	global_load_dwordx4 v[200:203], v[72:73], off offset:576
	v_lshl_add_u64 v[70:71], s[48:49], 0, v[70:71]
	v_lshl_add_u64 v[70:71], v[70:71], 0, v[170:171]
	s_movk_i32 s0, 0x7f6f
	v_cmp_lt_i32_e32 vcc, s0, v168
	s_waitcnt vmcnt(3)
	v_pk_fma_f32 v[64:65], v[64:65], v[132:133], v[190:191]
	v_pk_fma_f32 v[62:63], v[62:63], v[130:131], v[188:189]
	global_store_dwordx4 v[70:71], v[62:65], off
	s_waitcnt vmcnt(3)
	v_pk_fma_f32 v[60:61], v[60:61], v[128:129], v[194:195]
	v_pk_fma_f32 v[58:59], v[58:59], v[126:127], v[192:193]
	global_store_dwordx4 v[70:71], v[58:61], off offset:64
	s_waitcnt vmcnt(3)
	v_pk_fma_f32 v[56:57], v[56:57], v[120:121], v[198:199]
	v_pk_fma_f32 v[54:55], v[54:55], v[118:119], v[196:197]
	global_store_dwordx4 v[70:71], v[54:57], off offset:512
	s_waitcnt vmcnt(3)
	v_pk_fma_f32 v[52:53], v[52:53], v[116:117], v[202:203]
	v_add_u32_e32 v54, 0x90, v168
	v_pk_fma_f32 v[50:51], v[50:51], v[114:115], v[200:201]
	global_store_dwordx4 v[70:71], v[50:53], off offset:576
	s_and_saveexec_b64 s[0:1], vcc
	s_xor_b64 s[0:1], exec, s[0:1]
	v_add_u32_e32 v50, 0xffff8090, v168
	v_mov_b32_e32 v51, v0
	v_lshlrev_b64 v[50:51], 12, v[50:51]
	v_mov_b32_e32 v55, v0
	v_lshl_add_u64 v[50:51], s[6:7], 0, v[50:51]
	v_lshlrev_b64 v[52:53], 12, v[54:55]
	s_andn2_saveexec_b64 s[0:1], s[0:1]
	v_ashrrev_i32_e32 v55, 31, v54
	v_lshlrev_b64 v[52:53], 12, v[54:55]
	v_lshl_add_u64 v[50:51], s[48:49], 0, v[52:53]
	s_or_b64 exec, exec, s[0:1]
	v_lshl_add_u64 v[50:51], v[50:51], 0, v[170:171]
	global_load_dwordx4 v[188:191], v[50:51], off
	global_load_dwordx4 v[192:195], v[50:51], off offset:64
	global_load_dwordx4 v[196:199], v[50:51], off offset:512
	global_load_dwordx4 v[200:203], v[50:51], off offset:576
	v_lshl_add_u64 v[52:53], s[48:49], 0, v[52:53]
	v_lshl_add_u64 v[52:53], v[52:53], 0, v[170:171]
	s_movk_i32 s0, 0x7f5f
	v_cmp_lt_i32_e32 vcc, s0, v168
	s_waitcnt vmcnt(3)
;     __device__ __forceinline__ void operator()(const f32x4 (&acc)[2][2][4][2], const Unit& u, int wr, int wc, int fr, int fq) const {
;     ...
;             for (int m = 0; m < 4; ++m) { const int row = row0 + ai * HALF + m * 16;
;                 const float* bp = row < 32768 ? base_a + (size_t)row * 1024 : base_b + (size_t)(row - 32768) * 1024; float* op = out + (size_t)row * 1024;
; #pragma unroll
;                 for (int bj = 0; bj < 2; ++bj)
; #pragma unroll
;                     for (int n = 0; n < 2; ++n) { const int c = col0 + bj * HALF + n * 16; const f32x4 o = *(const f32x4*)(bp + c) + gv[bj][n] * acc[ai][bj][m][n]; *(f32x4*)(op + c) = o; }
;                 if (m & 1) asm volatile("" ::: "memory"); }
; template <class Epi, class Sched, bool ALIGN_EPI = false, bool SP2 = false>
; __device__ __forceinline__ void gemm_phase(PG8_LAS unsigned char* lds, const Gemm g, const Sched& S, const Epi& E, int tid_in) {
;     ...
;         if constexpr (!Epi::AFTER_DRAIN) { E(acc, cur, wr, wc, fr, fq); S.done(cur); }
;         if (!has_next) break;
	v_pk_fma_f32 v[48:49], v[48:49], v[132:133], v[190:191]
	v_pk_fma_f32 v[46:47], v[46:47], v[130:131], v[188:189]
	global_store_dwordx4 v[52:53], v[46:49], off
	s_waitcnt vmcnt(3)
	v_pk_fma_f32 v[44:45], v[44:45], v[128:129], v[194:195]
	v_pk_fma_f32 v[42:43], v[42:43], v[126:127], v[192:193]
	global_store_dwordx4 v[52:53], v[42:45], off offset:64
	s_waitcnt vmcnt(3)
	v_pk_fma_f32 v[40:41], v[40:41], v[120:121], v[198:199]
	v_pk_fma_f32 v[38:39], v[38:39], v[118:119], v[196:197]
	global_store_dwordx4 v[52:53], v[38:41], off offset:512
	s_waitcnt vmcnt(3)
	v_pk_fma_f32 v[36:37], v[36:37], v[116:117], v[202:203]
	v_pk_fma_f32 v[34:35], v[34:35], v[114:115], v[200:201]
	global_store_dwordx4 v[52:53], v[34:37], off offset:576
	s_nop 1
	v_add_u32_e32 v34, 0xa0, v168
	s_and_saveexec_b64 s[0:1], vcc
	s_xor_b64 s[0:1], exec, s[0:1]
	v_add_u32_e32 v36, 0xffff80a0, v168
	v_mov_b32_e32 v37, v0
	v_lshlrev_b64 v[36:37], 12, v[36:37]
	v_mov_b32_e32 v35, v0
	v_lshl_add_u64 v[36:37], s[6:7], 0, v[36:37]
	v_lshlrev_b64 v[38:39], 12, v[34:35]
	s_andn2_saveexec_b64 s[0:1], s[0:1]
	v_ashrrev_i32_e32 v35, 31, v34
	v_lshlrev_b64 v[38:39], 12, v[34:35]
	v_lshl_add_u64 v[36:37], s[48:49], 0, v[38:39]
	s_or_b64 exec, exec, s[0:1]
	v_lshl_add_u64 v[40:41], v[36:37], 0, v[170:171]
	global_load_dwordx4 v[188:191], v[40:41], off
	global_load_dwordx4 v[192:195], v[40:41], off offset:64
	global_load_dwordx4 v[196:199], v[40:41], off offset:512
	global_load_dwordx4 v[200:203], v[40:41], off offset:576
	v_lshl_add_u64 v[38:39], s[48:49], 0, v[38:39]
	v_lshl_add_u64 v[38:39], v[38:39], 0, v[170:171]
	s_movk_i32 s0, 0x7f4f
	v_cmp_lt_i32_e32 vcc, s0, v168
	s_waitcnt vmcnt(3)
	v_pk_fma_f32 v[32:33], v[32:33], v[132:133], v[190:191]
	v_pk_fma_f32 v[30:31], v[30:31], v[130:131], v[188:189]
	global_store_dwordx4 v[38:39], v[30:33], off
	s_waitcnt vmcnt(3)
	v_pk_fma_f32 v[28:29], v[28:29], v[128:129], v[194:195]
	v_pk_fma_f32 v[26:27], v[26:27], v[126:127], v[192:193]
	global_store_dwordx4 v[38:39], v[26:29], off offset:64
	s_waitcnt vmcnt(3)
	v_pk_fma_f32 v[24:25], v[24:25], v[120:121], v[198:199]
	v_pk_fma_f32 v[22:23], v[22:23], v[118:119], v[196:197]
	global_store_dwordx4 v[38:39], v[22:25], off offset:512
	s_waitcnt vmcnt(3)
	v_pk_fma_f32 v[20:21], v[20:21], v[116:117], v[202:203]
	v_add_u32_e32 v22, 0xb0, v168
	v_pk_fma_f32 v[18:19], v[18:19], v[114:115], v[200:201]
	global_store_dwordx4 v[38:39], v[18:21], off offset:576
	s_and_saveexec_b64 s[0:1], vcc
	s_xor_b64 s[0:1], exec, s[0:1]
	v_add_u32_e32 v18, 0xffff80b0, v168
	v_mov_b32_e32 v19, v0
	v_lshlrev_b64 v[18:19], 12, v[18:19]
	v_mov_b32_e32 v23, v0
	v_lshl_add_u64 v[18:19], s[6:7], 0, v[18:19]
	v_lshlrev_b64 v[20:21], 12, v[22:23]
	s_andn2_saveexec_b64 s[0:1], s[0:1]
	v_ashrrev_i32_e32 v23, 31, v22
	v_lshlrev_b64 v[20:21], 12, v[22:23]
	v_lshl_add_u64 v[18:19], s[48:49], 0, v[20:21]
	s_or_b64 exec, exec, s[0:1]
	v_lshl_add_u64 v[18:19], v[18:19], 0, v[170:171]
	global_load_dwordx4 v[188:191], v[18:19], off
	global_load_dwordx4 v[192:195], v[18:19], off offset:64
	global_load_dwordx4 v[196:199], v[18:19], off offset:512
	global_load_dwordx4 v[200:203], v[18:19], off offset:576
	v_lshl_add_u64 v[20:21], s[48:49], 0, v[20:21]
	v_lshl_add_u64 v[20:21], v[20:21], 0, v[170:171]
	s_and_b64 vcc, exec, s[42:43]
	s_mov_b64 s[0:1], -1
	s_waitcnt vmcnt(3)
	v_pk_fma_f32 v[16:17], v[16:17], v[132:133], v[190:191]
	v_pk_fma_f32 v[14:15], v[14:15], v[130:131], v[188:189]
	global_store_dwordx4 v[20:21], v[14:17], off
	s_waitcnt vmcnt(3)
	v_pk_fma_f32 v[12:13], v[12:13], v[128:129], v[194:195]
	v_pk_fma_f32 v[10:11], v[10:11], v[126:127], v[192:193]
	global_store_dwordx4 v[20:21], v[10:13], off offset:64
	s_waitcnt vmcnt(3)
	v_pk_fma_f32 v[8:9], v[8:9], v[120:121], v[198:199]
	v_pk_fma_f32 v[6:7], v[6:7], v[118:119], v[196:197]
	global_store_dwordx4 v[20:21], v[6:9], off offset:512
	s_waitcnt vmcnt(3)
	v_pk_fma_f32 v[4:5], v[4:5], v[116:117], v[202:203]
	v_pk_fma_f32 v[2:3], v[2:3], v[114:115], v[200:201]
	global_store_dwordx4 v[20:21], v[2:5], off offset:576
	s_cbranch_vccnz .LBB0_1107
	s_andn2_b64 vcc, exec, s[2:3]
	s_cbranch_vccnz .LBB0_1106
	s_barrier
	s_branch .LBB0_1106
